# ADIFF fast loop: static s_setprio 1 for waves 4-7 (younger half) on the split-QK / carry / weighted schedule
# speedup vs baseline: 1.0039x; 1.0039x over previous
; #define LAS __attribute__((address_space(3)))
; __device__ __forceinline__ void diff_attn_phase(const Params& p, LAS unsigned char* lds) {
;     ...
;                 for (int ks = 0; ks < 4; ++ks) kf[ks] = *(const LAS bf16x8*)(Ku + kbase + (kxl ^ (32 * ks)));
;                 bf16x8 P[2][2];
; #pragma unroll
;                 for (int r = 0; r < 2; ++r) {
;                     f32x16 S;
; #pragma unroll
;                     for (int i = 0; i < 16; ++i) S[i] = 0.f;
; #pragma unroll
;                     for (int ks = 0; ks < 4; ++ks) S = __builtin_amdgcn_mfma_f32_32x32x16_bf16(kf[ks], qf[r][ks], S, 0, 0, 0);
;                     S = __builtin_amdgcn_mfma_f32_32x32x16_bf16(kone, qm[r], S, 0, 0, 0);
; #pragma unroll
;                     for (int i = 0; i < 16; ++i) S[i] = __builtin_amdgcn_exp2f(S[i]);
;                     l[r] += sum16(S);
;                     P[r][0] = pack8(S, 0); P[r][1] = pack8(S, 8);
;                 }
; #pragma unroll
;                 for (int t = 0; t < 4; ++t) {
;                     const LAS unsigned char* a0 = Vu + (vb0l ^ (64 * t)); const LAS unsigned char* a1 = Vu + (vb1l ^ (64 * t));
;                     const bf16x8 v0 = tr_pair(a0, a1), v1 = tr_pair(a0 + 4096, a1 + 4096);
;                     O[0][t] = __builtin_amdgcn_mfma_f32_32x32x16_bf16(v0, P[0][0], O[0][t], 0, 0, 0);
;                     O[1][t] = __builtin_amdgcn_mfma_f32_32x32x16_bf16(v0, P[1][0], O[1][t], 0, 0, 0);
;                     O[0][t] = __builtin_amdgcn_mfma_f32_32x32x16_bf16(v1, P[0][1], O[0][t], 0, 0, 0);
;                     O[1][t] = __builtin_amdgcn_mfma_f32_32x32x16_bf16(v1, P[1][1], O[1][t], 0, 0, 0);
;                 }
;             }
;         }
.Lfb_last0F:
	s_waitcnt lgkmcnt(6)
	v_mfma_f32_32x32x16_bf16 v[114:129], v[198:201], v[222:225], v[114:129]
	v_exp_f32_e32 v130, v130
	v_exp_f32_e32 v131, v131
	v_mfma_f32_32x32x16_bf16 v[50:65], v[198:201], v[226:229], v[50:65]
	ds_read_b64_tr_b16 v[198:199], v234 offset:24576
	ds_read_b64_tr_b16 v[200:201], v235 offset:24576
	v_exp_f32_e32 v132, v132
	v_exp_f32_e32 v133, v133
	s_waitcnt lgkmcnt(6)
	v_mfma_f32_32x32x16_bf16 v[98:113], v[202:205], v[222:225], v[98:113]
	v_add_f32_e32 v212, v212, v130
	v_add_f32_e32 v212, v212, v131
	v_add_f32_e32 v212, v212, v132
	v_add_f32_e32 v212, v212, v133
	v_mfma_f32_32x32x16_bf16 v[34:49], v[202:205], v[226:229], v[34:49]
	ds_read_b64_tr_b16 v[202:203], v237 offset:24576
	ds_read_b64_tr_b16 v[204:205], v236 offset:24576
	v_exp_f32_e32 v134, v134
	v_exp_f32_e32 v135, v135
	s_waitcnt lgkmcnt(6)
	v_mfma_f32_32x32x16_bf16 v[82:97], v[208:211], v[222:225], v[82:97]
	v_exp_f32_e32 v136, v136
	v_exp_f32_e32 v137, v137
	v_mfma_f32_32x32x16_bf16 v[18:33], v[208:211], v[226:229], v[18:33]
	ds_read_b64_tr_b16 v[208:209], v238 offset:24576
	ds_read_b64_tr_b16 v[210:211], v239 offset:24576
	v_add_f32_e32 v212, v212, v134
	v_add_f32_e32 v212, v212, v135
	v_add_f32_e32 v212, v212, v136
	v_add_f32_e32 v212, v212, v137
	s_waitcnt lgkmcnt(6)
	v_mfma_f32_32x32x16_bf16 v[66:81], v[230:233], v[222:225], v[66:81]
	v_cvt_pk_bf16_f32 v214, v146, v147
	v_cvt_pk_bf16_f32 v215, v148, v149
	v_cvt_pk_bf16_f32 v216, v150, v151
	v_cvt_pk_bf16_f32 v217, v152, v153
	v_cvt_pk_bf16_f32 v218, v130, v131
	v_cvt_pk_bf16_f32 v219, v132, v133
	v_cvt_pk_bf16_f32 v220, v134, v135
	v_cvt_pk_bf16_f32 v221, v136, v137
	v_cvt_pk_bf16_f32 v222, v154, v155
	v_cvt_pk_bf16_f32 v223, v156, v157
	v_cvt_pk_bf16_f32 v224, v158, v159
	v_cvt_pk_bf16_f32 v225, v160, v161
	v_mfma_f32_32x32x16_bf16 v[2:17], v[230:233], v[226:229], v[2:17]
	ds_read_b64_tr_b16 v[230:231], v250 offset:24576
	ds_read_b64_tr_b16 v[232:233], v251 offset:24576
	v_exp_f32_e32 v138, v138
	v_exp_f32_e32 v139, v139
	v_exp_f32_e32 v140, v140
	v_exp_f32_e32 v141, v141
	v_add_f32_e32 v212, v212, v138
	v_add_f32_e32 v212, v212, v139
	v_add_f32_e32 v212, v212, v140
	v_add_f32_e32 v212, v212, v141
	v_exp_f32_e32 v142, v142
	v_exp_f32_e32 v143, v143
	v_exp_f32_e32 v144, v144
	v_exp_f32_e32 v145, v145
	v_add_f32_e32 v212, v212, v142
	v_add_f32_e32 v212, v212, v143
	v_add_f32_e32 v212, v212, v144
	v_add_f32_e32 v212, v212, v145
	v_cvt_pk_bf16_f32 v226, v138, v139
	v_cvt_pk_bf16_f32 v227, v140, v141
	v_cvt_pk_bf16_f32 v228, v142, v143
	v_cvt_pk_bf16_f32 v229, v144, v145
	s_waitcnt lgkmcnt(6)
	v_mfma_f32_32x32x16_bf16 v[114:129], v[198:201], v[214:217], v[114:129]
	v_mfma_f32_32x32x16_bf16 v[50:65], v[198:201], v[218:221], v[50:65]
	ds_read_b64_tr_b16 v[198:199], v234 offset:28672
	ds_read_b64_tr_b16 v[200:201], v235 offset:28672
	s_waitcnt lgkmcnt(6)
	v_mfma_f32_32x32x16_bf16 v[98:113], v[202:205], v[214:217], v[98:113]
	v_mfma_f32_32x32x16_bf16 v[34:49], v[202:205], v[218:221], v[34:49]
	ds_read_b64_tr_b16 v[202:203], v237 offset:28672
	ds_read_b64_tr_b16 v[204:205], v236 offset:28672
	s_waitcnt lgkmcnt(6)
	v_mfma_f32_32x32x16_bf16 v[82:97], v[208:211], v[214:217], v[82:97]
	v_mfma_f32_32x32x16_bf16 v[18:33], v[208:211], v[218:221], v[18:33]
	ds_read_b64_tr_b16 v[208:209], v238 offset:28672
	ds_read_b64_tr_b16 v[210:211], v239 offset:28672
	s_waitcnt lgkmcnt(6)
	v_mfma_f32_32x32x16_bf16 v[66:81], v[230:233], v[214:217], v[66:81]
	v_mfma_f32_32x32x16_bf16 v[2:17], v[230:233], v[218:221], v[2:17]
	ds_read_b64_tr_b16 v[230:231], v250 offset:28672
	ds_read_b64_tr_b16 v[232:233], v251 offset:28672
	s_waitcnt lgkmcnt(6)
	v_mfma_f32_32x32x16_bf16 v[114:129], v[198:201], v[222:225], v[114:129]
	v_mfma_f32_32x32x16_bf16 v[50:65], v[198:201], v[226:229], v[50:65]
	s_waitcnt lgkmcnt(4)
	v_mfma_f32_32x32x16_bf16 v[98:113], v[202:205], v[222:225], v[98:113]
	v_mfma_f32_32x32x16_bf16 v[34:49], v[202:205], v[226:229], v[34:49]
	s_waitcnt lgkmcnt(2)
	v_mfma_f32_32x32x16_bf16 v[82:97], v[208:211], v[222:225], v[82:97]
	v_mfma_f32_32x32x16_bf16 v[18:33], v[208:211], v[226:229], v[18:33]
	s_waitcnt lgkmcnt(0)
	v_mfma_f32_32x32x16_bf16 v[66:81], v[230:233], v[222:225], v[66:81]
	v_mfma_f32_32x32x16_bf16 v[2:17], v[230:233], v[226:229], v[2:17]
	s_setprio 0
	s_branch .Lad_epi
